# v61: v59 + placement check (workgroup XCD id vs bid&7, published at step 0): if any workgroup sits on an unexpected XCD every panel hand-off writes back L2 first
# baseline (speedup 1.0000x reference)
.LBB0_9:
	s_mul_i32 s3, s6, 3
	s_getpc_b64 s[0:1]
	s_add_u32 s0, s0, PROG@rel32@lo+4
	s_addc_u32 s1, s1, PROG@rel32@hi+12
	s_and_b32 s2, s3, -4
	s_add_u32 s0, s0, s2
	s_addc_u32 s1, s1, 0
	s_load_dwordx2 s[0:1], s[0:1], 0x0
	s_and_b32 s3, s3, 3
	s_lshl_b32 s3, s3, 3
	s_waitcnt lgkmcnt(0)
	s_lshr_b64 s[0:1], s[0:1], s3
	s_and_b32 s2, s0, 0xffff
	v_mov_b32_e32 v0, s2
	s_bfe_u32 s2, s0, 0x80010
	v_mov_b32_e32 v2, s2
	s_cmp_gt_u32 s6, 1
	s_cbranch_scc1 .Lsm_done
	v_readlane_b32 s0, v254, 39
	v_readlane_b32 s1, v254, 40
	s_add_u32 s0, s0, 0xc000
	s_addc_u32 s1, s1, 0
	s_cmp_eq_u32 s6, 1
	s_cbranch_scc1 .Lsm_cache
	s_getreg_b32 s2, hwreg(HW_REG_XCC_ID, 0, 4)
	s_and_b32 s2, s2, 15
	s_and_b32 s3, s66, 7
	s_cmp_eq_u32 s2, s3
	s_cbranch_scc1 .Lsm_done
	s_mov_b64 s[2:3], exec
	s_mov_b64 exec, 1
	global_atomic_add v1, v226, s[0:1]
	s_mov_b64 exec, s[2:3]
	s_branch .Lsm_done
.Lsm_cache:
	global_load_dword v3, v1, s[0:1] sc1
	s_waitcnt vmcnt(0)
	v_readfirstlane_b32 s2, v3
	s_nop 1
	v_writelane_b32 v255, s2, 63
.Lsm_done:
	s_mov_b32 s7, s63
	v_writelane_b32 v254, s6, 61
	s_mov_b32 s67, s66
	s_mov_b64 s[8:9], -1
	v_writelane_b32 v254, s7, 62
	s_waitcnt vmcnt(0) lgkmcnt(0)
	v_lshrrev_b32_e32 v3, 8, v0
	v_readlane_b32 s0, v254, 4
	v_readlane_b32 s60, v254, 0
	v_readlane_b32 s61, v254, 1
	v_writelane_b32 v254, s0, 63
	s_waitcnt vmcnt(0)
	v_readfirstlane_b32 s0, v2
	s_load_dwordx4 s[16:19], s[60:61], 0x108
	s_add_u32 s10, s60, 0x108
	v_writelane_b32 v255, s0, 0
	s_mov_b64 s[0:1], 0
	v_writelane_b32 v255, s0, 1
	s_addc_u32 s11, s61, 0
	v_and_b32_e32 v0, 0xff, v0
	v_writelane_b32 v255, s1, 2
	v_writelane_b32 v255, s10, 3
	v_readfirstlane_b32 s2, v0
	v_readfirstlane_b32 s80, v3
	v_writelane_b32 v255, s11, 4
	s_waitcnt lgkmcnt(0)
	s_add_u32 s10, s18, 0xb800000
	v_writelane_b32 v255, s16, 5
	s_addc_u32 s11, s19, 0
	s_cmp_lt_i32 s2, 9
	v_writelane_b32 v255, s17, 6
	v_writelane_b32 v255, s18, 7
	v_writelane_b32 v255, s19, 8
	v_writelane_b32 v255, s10, 9
	s_nop 1
	v_writelane_b32 v255, s11, 10
	v_writelane_b32 v255, s2, 11
	s_mov_b64 s[2:3], 0
	v_writelane_b32 v255, s2, 12
	s_nop 1
	v_writelane_b32 v255, s3, 13
	s_mov_b64 s[2:3], 0
	s_cbranch_scc1 .LBB0_142
	v_readlane_b32 s0, v255, 11
	s_cmp_gt_i32 s0, 12
	s_cbranch_scc0 .LBB0_17
	v_writelane_b32 v255, s2, 16
	s_cmp_gt_i32 s0, 14
	s_mov_b64 s[22:23], -1
	v_writelane_b32 v255, s3, 17
	s_mov_b64 s[0:1], 0
	v_writelane_b32 v255, s0, 12
	s_mov_b64 s[2:3], 0
	s_mov_b64 s[6:7], -1
	v_writelane_b32 v255, s1, 13
	s_cbranch_scc0 .LBB0_113
	s_mov_b64 s[0:1], 0
	v_writelane_b32 v255, s0, 12
	s_nop 1
	v_writelane_b32 v255, s1, 13
	s_nop 0
	v_readlane_b32 s0, v255, 11
	s_cmp_gt_i32 s0, 15
	s_cbranch_scc0 .LBB0_111
	v_readlane_b32 s0, v255, 11
	s_cmp_gt_i32 s0, 16
	s_mov_b64 s[2:3], -1
	s_cbranch_scc0 .LBB0_28
	s_cmp_eq_u32 s0, 17
	s_cbranch_scc0 .LBB0_27
	s_lshl_b32 s0, s67, 3
	v_readlane_b32 s1, v254, 63
	s_add_i32 s6, s0, s1
	v_mov_b32_e32 v0, v1
	s_cmpk_gt_i32 s6, 0x2fff
	s_cbranch_scc1 .LBB0_27
	v_mbcnt_lo_u32_b32 v0, -1, v0
	s_load_dwordx2 s[0:1], s[60:61], 0x60
	v_mbcnt_hi_u32_b32 v0, -1, v0
	v_lshlrev_b32_e32 v18, 2, v0
	v_ashrrev_i32_e32 v19, 31, v18
	v_lshlrev_b64 v[20:21], 2, v[18:19]
	s_waitcnt lgkmcnt(0)
	v_lshl_add_u64 v[14:15], s[0:1], 0, v[20:21]
	global_load_dwordx4 v[2:5], v[14:15], off
	global_load_dwordx4 v[6:9], v[14:15], off offset:1024
	global_load_dwordx4 v[10:13], v[14:15], off offset:2048
	s_nop 0
	global_load_dwordx4 v[14:17], v[14:15], off offset:3072
	s_load_dwordx4 s[0:3], s[60:61], 0x108
	v_xor_b32_e32 v0, 4, v18
	v_xor_b32_e32 v70, 8, v18
	v_xor_b32_e32 v71, 16, v18
	v_xor_b32_e32 v72, 32, v18
	s_waitcnt lgkmcnt(0)
	v_lshl_add_u64 v[66:67], s[0:1], 0, v[20:21]
	v_xor_b32_e32 v73, 64, v18
	v_xor_b32_e32 v74, 0x80, v18
	s_branch .LBB0_19

.Lrf_j1:
	s_barrier
	s_cmp_lg_u32 s3, 0
	s_cbranch_scc1 .Lrf_bar
	v_readlane_b32 s2, v254, 61
	s_lshl_b32 s2, s2, 8
	s_lshl_b32 s8, s17, 2
	s_add_i32 s2, s2, s8
	s_add_i32 s2, s2, 0x10000
	v_readlane_b32 s8, v255, 7
	v_readlane_b32 s9, v255, 8
	s_add_u32 s8, s8, s2
	s_addc_u32 s9, s9, 0
	v_readlane_b32 s12, v255, 63
	s_cmp_eq_u32 s12, 0
	s_cbranch_scc1 .Lrf_local
	buffer_wbl2 sc1
	s_waitcnt vmcnt(0)
.Lrf_local:
	s_mov_b64 s[14:15], exec
	s_mov_b64 exec, 1
	global_atomic_add v1, v226, s[8:9]
	s_mov_b64 exec, s[14:15]
	s_mov_b32 s2, 0

.LBB0_798:
	s_waitcnt vmcnt(0)
	v_readlane_b32 s76, v254, 39
	v_readlane_b32 s84, v254, 46
	v_readlane_b32 s94, v254, 52
	v_readlane_b32 s56, v254, 54
	v_readlane_b32 s18, v254, 61
	v_readlane_b32 s58, v255, 22
	v_readlane_b32 s60, v255, 14
	v_readlane_b32 s68, v255, 32
	v_readlane_b32 s70, v255, 34
	v_readlane_b32 s66, v254, 38
	v_readlane_b32 s77, v254, 40
	v_readlane_b32 s78, v254, 41
	v_readlane_b32 s92, v254, 43
	s_movk_i32 s93, 0x80
	v_readlane_b32 s96, v254, 44
	v_readlane_b32 s85, v254, 47
	v_readlane_b32 s95, v254, 53
	v_readlane_b32 s57, v254, 55
	v_readlane_b32 s29, v254, 56
	v_readlane_b32 s35, v254, 57
	v_readlane_b32 s38, v254, 58
	s_mov_b32 s39, 0x12000
	s_movk_i32 s40, 0x3000
	s_mov_b32 s41, 0x18000
	s_mov_b32 s42, 0x9000
	s_movk_i32 s43, 0xffe0
	s_mov_b32 s44, 0x28000
	s_mov_b32 s45, 0x7f800000
	s_mov_b64 s[50:51], 0x48000
	v_readlane_b32 s19, v254, 62
	v_readlane_b32 s59, v255, 23
	v_readlane_b32 s61, v255, 15
	v_readlane_b32 s67, v255, 26
	v_readlane_b32 s80, v255, 29
	v_readlane_b32 s69, v255, 33
	v_readlane_b32 s71, v255, 35
	s_barrier
	v_readlane_b32 s0, v255, 0
	s_cmp_lg_u32 s0, 0
	s_cbranch_scc1 .Lfz_nosig
	v_readlane_b32 s0, v255, 11
	s_cmp_eq_u32 s0, 4
	s_cselect_b32 s1, 1, 0
	s_cmp_eq_u32 s0, 8
	s_cselect_b32 s1, 1, s1
	s_cmp_eq_u32 s1, 0
	s_cbranch_scc1 .Lfz_nosig
	s_cmpk_gt_i32 s67, 191
	s_cbranch_scc1 .Lfz_nosig
	v_readlane_b32 s0, v254, 63
	s_cmp_lg_u32 s0, 0
	s_cbranch_scc1 .Lfz_nosig
	s_and_b32 s0, s67, 7
	s_mul_i32 s0, s0, 6
	s_lshr_b32 s1, s67, 3
	s_mul_i32 s2, s1, 43
	s_lshr_b32 s2, s2, 8
	s_mul_i32 s3, s2, 6
	s_sub_i32 s1, s1, s3
	s_add_i32 s0, s0, s1
	s_lshl_b32 s0, s0, 2
	s_lshl_b32 s1, s18, 8
	s_add_i32 s0, s0, s1
	s_add_i32 s0, s0, 0x10000
	v_readlane_b32 s2, v255, 7
	v_readlane_b32 s3, v255, 8
	s_add_u32 s2, s2, s0
	s_addc_u32 s3, s3, 0
	v_readlane_b32 s0, v255, 63
	s_cmp_eq_u32 s0, 0
	s_cbranch_scc1 .Lfz_local
	buffer_wbl2 sc1
	s_waitcnt vmcnt(0)
.Lfz_local:
	s_mov_b64 s[0:1], exec
	s_mov_b64 exec, 1
	global_atomic_add v1, v226, s[2:3]
	s_mov_b64 exec, s[0:1]
